# NSA unit: sliding-window branch tiles 0/1 prefetched into free VGPRs before the top-16 selection (latency hidden behind selection + selected branch)
# speedup vs baseline: 1.0140x; 1.0140x over previous
; DI unsigned cvtpk(float lo, float hi) { f32x2_t v = {lo, hi}; bf16x2_t b = __builtin_convertvector(v, bf16x2_t); return __builtin_bit_cast(unsigned, b); }
; #define MFMA32(a, b, c) __builtin_amdgcn_mfma_f32_32x32x16_bf16((a), (b), (c), 0, 0, 0)
; #define SBAR() __builtin_amdgcn_sched_barrier(0)
; template <int VSTR, int NDVB> DI void pv64(f32x16 (&O)[NDVB], const lds8* vp, const bf16x8 (&P)[4]) {
;   bf16x8 f[2][NDVB];
; #pragma unroll
;   for (int d = 0; d < NDVB; ++d) { const s16x4 lo = trrd(vp + d * 64), hi = trrd(vp + 8 * VSTR + d * 64); f[0][d] = __builtin_shufflevector(lo, hi, 0, 1, 2, 3, 4, 5, 6, 7); }
; #pragma unroll
;   for (int kk = 0; kk < 4; ++kk) {
;     if (kk < 3) {
; #pragma unroll
;       for (int d = 0; d < NDVB; ++d) { const s16x4 lo = trrd(vp + (16 * (kk + 1)) * VSTR + d * 64), hi = trrd(vp + (16 * (kk + 1) + 8) * VSTR + d * 64);
;         f[(kk + 1) & 1][d] = __builtin_shufflevector(lo, hi, 0, 1, 2, 3, 4, 5, 6, 7); }
;     }
;     SBAR();
;     __builtin_amdgcn_s_setprio(1);
; #pragma unroll
;     for (int d = 0; d < NDVB; ++d) O[d] = MFMA32(f[kk & 1][d], P[kk], O[d]);
;     __builtin_amdgcn_s_setprio(0);
;     SBAR();
;   }
; }
; template <int NDVB, bool HAS_NEXT> DI void softmax_def(f32x16& sa0, f32x16& sa1, f32x16& sb0, f32x16& sb1, f32x16 (&O)[NDVB], float& muse, float& l, bool first, bf16x8 (&P)[4], bool check = true) {
;     ...
;   float sum = 0.f;
; #pragma unroll
;   for (int i = 0; i < 16; ++i) { sa0[i] = __builtin_amdgcn_exp2f(sa0[i]); sum += sa0[i]; }
; #pragma unroll
;   for (int i = 0; i < 16; ++i) { sa1[i] = __builtin_amdgcn_exp2f(sa1[i]); sum += sa1[i]; }
;   l += sum;
;   u32x4 w;
;   w.x = cvtpk(sa0[0], sa0[1]); w.y = cvtpk(sa0[2], sa0[3]); w.z = cvtpk(sa0[4], sa0[5]); w.w = cvtpk(sa0[6], sa0[7]); P[0] = __builtin_bit_cast(bf16x8, w);
;   w.x = cvtpk(sa0[8], sa0[9]); w.y = cvtpk(sa0[10], sa0[11]); w.z = cvtpk(sa0[12], sa0[13]); w.w = cvtpk(sa0[14], sa0[15]); P[1] = __builtin_bit_cast(bf16x8, w);
;   w.x = cvtpk(sa1[0], sa1[1]); w.y = cvtpk(sa1[2], sa1[3]); w.z = cvtpk(sa1[4], sa1[5]); w.w = cvtpk(sa1[6], sa1[7]); P[2] = __builtin_bit_cast(bf16x8, w);
;   w.x = cvtpk(sa1[8], sa1[9]); w.y = cvtpk(sa1[10], sa1[11]); w.z = cvtpk(sa1[12], sa1[13]); w.w = cvtpk(sa1[14], sa1[15]); P[3] = __builtin_bit_cast(bf16x8, w);
.LBB0_903:
	v_lshlrev_b32_e32 v217, 3, v55
	v_add_f32_e32 v0, v97, v98
	v_add_f32_e32 v55, v99, v56
	v_add_f32_e32 v121, v0, v55
	v_add_f32_e32 v0, v109, v110
	v_add_f32_e32 v55, v111, v60
	v_add_f32_e32 v97, v0, v55
	v_add_f32_e32 v0, v100, v101
	v_add_f32_e32 v55, v102, v57
	v_add_f32_e32 v101, v0, v55
	v_add_f32_e32 v0, v112, v113
	v_add_f32_e32 v55, v114, v61
	v_add_f32_e32 v98, v0, v55
	v_add_f32_e32 v0, v103, v104
	v_add_f32_e32 v55, v105, v58
	v_exp_f32_e32 v50, v50
	v_add_f32_e32 v100, v0, v55
	v_add_f32_e32 v0, v115, v116
	v_add_f32_e32 v55, v117, v62
	v_exp_f32_e32 v51, v51
	v_add_f32_e32 v55, v0, v55
	v_add_f32_e32 v0, v106, v107
	v_add_f32_e32 v99, v108, v59
	v_exp_f32_e32 v103, v18
	v_add_f32_e32 v99, v0, v99
	v_add_f32_e32 v0, v118, v119
	v_add_f32_e32 v102, v120, v63
	v_exp_f32_e32 v18, v19
	v_add_f32_e32 v0, v0, v102
	v_add_f32_e32 v102, 0, v50
	v_add_f32_e32 v102, v51, v102
	v_add_f32_e32 v102, v103, v102
	v_add_f32_e32 v19, v18, v102
	v_exp_f32_e32 v102, v20
	v_exp_f32_e32 v21, v21
	v_exp_f32_e32 v22, v22
	v_exp_f32_e32 v104, v2
	v_add_f32_e32 v19, v102, v19
	v_add_f32_e32 v19, v21, v19
	v_add_f32_e32 v20, v22, v19
	v_exp_f32_e32 v19, v23
	v_exp_f32_e32 v23, v24
	v_exp_f32_e32 v24, v25
	v_exp_f32_e32 v25, v26
	v_add_f32_e32 v20, v19, v20
	v_add_f32_e32 v20, v23, v20
	v_add_f32_e32 v20, v24, v20
	v_add_f32_e32 v26, v25, v20
	v_exp_f32_e32 v20, v27
	v_exp_f32_e32 v27, v28
	v_exp_f32_e32 v28, v29
	v_exp_f32_e32 v29, v30
	v_add_f32_e32 v26, v20, v26
	v_exp_f32_e32 v30, v31
	v_add_f32_e32 v26, v27, v26
	v_exp_f32_e32 v31, v16
	v_add_f32_e32 v26, v28, v26
	v_add_f32_e32 v26, v29, v26
	v_add_f32_e32 v26, v30, v26
	v_add_f32_e32 v16, v31, v26
	v_exp_f32_e32 v26, v17
	v_exp_f32_e32 v110, v3
	v_exp_f32_e32 v105, v4
	v_exp_f32_e32 v106, v5
	v_add_f32_e32 v16, v26, v16
	v_add_f32_e32 v2, v104, v16
	v_exp_f32_e32 v107, v6
	v_add_f32_e32 v2, v110, v2
	v_exp_f32_e32 v111, v7
	v_add_f32_e32 v2, v105, v2
	v_exp_f32_e32 v108, v8
	v_add_f32_e32 v2, v106, v2
	v_exp_f32_e32 v109, v9
	v_add_f32_e32 v2, v107, v2
	v_exp_f32_e32 v112, v10
	v_add_f32_e32 v2, v111, v2
	v_exp_f32_e32 v113, v11
	v_add_f32_e32 v2, v108, v2
	v_exp_f32_e32 v114, v12
	v_add_f32_e32 v2, v109, v2
	v_exp_f32_e32 v115, v13
	v_add_f32_e32 v2, v112, v2
	v_exp_f32_e32 v116, v14
	v_add_f32_e32 v2, v113, v2
	v_exp_f32_e32 v117, v15
	v_add_f32_e32 v2, v114, v2
	v_add_f32_e32 v2, v115, v2
	v_add_f32_e32 v2, v116, v2
	v_add_f32_e32 v2, v117, v2
	v_cvt_pk_bf16_f32 v4, v102, v21
	v_cvt_pk_bf16_f32 v5, v22, v19
	v_cvt_pk_bf16_f32 v10, v31, v26
	v_add_f32_e32 v26, v26, v31
	v_add_f32_e32 v31, v110, v104
	v_add_f32_e32 v21, v21, v102
	v_add_f32_e32 v22, v19, v22
	v_add_f32_e32 v48, v48, v2
	v_cvt_pk_bf16_f32 v2, v50, v51
	v_add_f32_e32 v50, v51, v50
	v_add_f32_e32 v51, v18, v103
	v_add_f32_e32 v31, v31, v26
	v_add_f32_e32 v21, v22, v21
	v_add_f32_e32 v22, v106, v105
	v_add_f32_e32 v26, v111, v107
	v_cvt_pk_bf16_f32 v6, v23, v24
	v_add_f32_e32 v50, v51, v50
	v_add_f32_e32 v51, v26, v22
	v_add_f32_e32 v22, v24, v23
	v_add_f32_e32 v23, v20, v25
	v_add_f32_e32 v118, v23, v22
	v_add_f32_e32 v22, v109, v108
	v_add_f32_e32 v23, v113, v112
	v_cvt_pk_bf16_f32 v15, v112, v113
	v_add_f32_e32 v112, v23, v22
	v_add_f32_e32 v22, v28, v27
	v_add_f32_e32 v23, v30, v29
	v_add_f32_e32 v119, v23, v22
	v_add_f32_e32 v22, v115, v114
	v_add_f32_e32 v23, v117, v116
	v_cvt_pk_bf16_f32 v3, v103, v18
	v_cvt_pk_bf16_f32 v7, v25, v20
	v_cvt_pk_bf16_f32 v8, v27, v28
	v_cvt_pk_bf16_f32 v9, v29, v30
	v_cvt_pk_bf16_f32 v11, v104, v110
	v_cvt_pk_bf16_f32 v12, v105, v106
	v_cvt_pk_bf16_f32 v13, v107, v111
	v_cvt_pk_bf16_f32 v14, v108, v109
	v_cvt_pk_bf16_f32 v16, v114, v115
	v_add_f32_e32 v114, v23, v22
	ds_read_b64_tr_b16 v[22:23], v96 offset:27648
	ds_read_b64_tr_b16 v[24:25], v96 offset:28800
	ds_read_b64_tr_b16 v[26:27], v96 offset:27712
	ds_read_b64_tr_b16 v[28:29], v96 offset:28864
	ds_read_b64_tr_b16 v[102:103], v96 offset:29952
	ds_read_b64_tr_b16 v[104:105], v96 offset:31104
	ds_read_b64_tr_b16 v[106:107], v96 offset:30016
	ds_read_b64_tr_b16 v[108:109], v96 offset:31168
	v_cvt_pk_bf16_f32 v17, v116, v117
	s_setprio 1
	s_waitcnt lgkmcnt(6)
	v_mfma_f32_32x32x16_bf16 v[80:95], v[22:25], v[2:5], v[80:95]
	s_waitcnt lgkmcnt(4)
	v_mfma_f32_32x32x16_bf16 v[64:79], v[26:29], v[2:5], v[64:79]
	s_setprio 0
	ds_read_b64_tr_b16 v[2:3], v96 offset:32256
	ds_read_b64_tr_b16 v[4:5], v96 offset:33408
	ds_read_b64_tr_b16 v[22:23], v96 offset:32320
	ds_read_b64_tr_b16 v[24:25], v96 offset:33472
	s_setprio 1
	s_waitcnt lgkmcnt(6)
	v_mfma_f32_32x32x16_bf16 v[80:95], v[102:105], v[6:9], v[80:95]
	s_waitcnt lgkmcnt(4)
	v_mfma_f32_32x32x16_bf16 v[64:79], v[106:109], v[6:9], v[64:79]
	s_setprio 0
	ds_read_b64_tr_b16 v[6:7], v96 offset:34560
	ds_read_b64_tr_b16 v[8:9], v96 offset:35712
	ds_read_b64_tr_b16 v[28:29], v96 offset:35776
	ds_read_b64_tr_b16 v[26:27], v96 offset:34624
	s_setprio 1
	s_waitcnt lgkmcnt(6)
	v_mfma_f32_32x32x16_bf16 v[80:95], v[2:5], v[10:13], v[80:95]
	s_waitcnt lgkmcnt(4)
	v_mfma_f32_32x32x16_bf16 v[64:79], v[22:25], v[10:13], v[64:79]
	s_setprio 0
	s_setprio 1
	s_waitcnt lgkmcnt(2)
	v_mfma_f32_32x32x16_bf16 v[80:95], v[6:9], v[14:17], v[80:95]
	s_waitcnt lgkmcnt(0)
	v_mfma_f32_32x32x16_bf16 v[64:79], v[26:29], v[14:17], v[64:79]
	s_setprio 0
	ds_bpermute_b32 v2, v193, v48
	v_readlane_b32 s1, v255, 39
	s_waitcnt lgkmcnt(0)
	s_barrier
; #define LAS __attribute__((address_space(3)))
; DI void nsa_unit(const Params& p, lds8* lds, int bl, int g, int qb32) {
;     ...
;   const float lt0 = l + __shfl_xor(l, 32); const float inv0 = lt0 > 0.f ? 1.f / lt0 : 0.f;
;   { const float f = g0 * inv0;
; #pragma unroll
;     for (int d = 0; d < 2; ++d)
; #pragma unroll
;       for (int i = 0; i < 16; ++i) OT[d][i] = O[d][i] * f; }
;   { LAS float* impw = (LAS float*)(lds + NS_IMPW) + (wid * 32 + r) * 33;
;     float carry = 0.f;
; #pragma unroll
;     for (int kt = 0; kt < 2; ++kt) {
;       const float scale = __builtin_amdgcn_exp2f(cap.mrec[kt] - m) * inv0;
; #pragma unroll
;       for (int kb = 0; kb < 2; ++kb)
; #pragma unroll
;         for (int ii = 0; ii < 4; ++ii) {
;           const float qsum = cap.qs[kt][kb * 4 + ii] * scale, last = cap.ls[kt][kb * 4 + ii] * scale;
;           const float other = __shfl_xor(last, 32);
;           const int ub = 16 * kt + 8 * kb + 2 * ii;
;           const float val = qsum + (h ? other : carry);
;           carry = other;
;           impw[ub + h] = val;
;         }
;     }
;   }
;   __syncthreads();
; #pragma unroll
;   for (int ks = 0; ks < 2; ++ks) {
;     const float* rc = rope + qpos * 32 + 16 * ks + 8 * h;
;     const f32x4 c0 = *(const f32x4*)rc, c1 = *(const f32x4*)(rc + 4), s0 = *(const f32x4*)(rc + 65536), s1 = *(const f32x4*)(rc + 65536 + 4);
	v_add_f32_e32 v2, v48, v2
	v_div_scale_f32 v3, s[8:9], v2, v2, 1.0
	v_rcp_f32_e32 v4, v3
	v_div_scale_f32 v5, vcc, 1.0, v2, 1.0
	v_readlane_b32 s8, v254, 63
	v_fma_f32 v6, -v3, v4, 1.0
	v_fmac_f32_e32 v4, v6, v4
	v_mul_f32_e32 v6, v5, v4
	v_fma_f32 v7, -v3, v6, v5
	v_fmac_f32_e32 v6, v7, v4
	v_fma_f32 v3, -v3, v6, v5
	v_div_fmas_f32 v3, v3, v4, v6
	v_sub_f32_e32 v4, v49, v1
	v_exp_f32_e32 v4, v4
	v_div_fixup_f32 v3, v3, v2, 1.0
	v_cmp_lt_f32_e32 vcc, 0, v2
	v_lshl_or_b32 v2, s1, 5, v52
	v_mul_lo_u32 v2, v2, s94
	v_cndmask_b32_e32 v218, 0, v3, vcc
	v_mul_f32_e32 v3, v4, v218
	v_mul_f32_e32 v4, v56, v3
	v_mul_f32_e32 v5, v57, v3
	ds_bpermute_b32 v4, v193, v4
	ds_bpermute_b32 v5, v193, v5
	v_mul_f32_e32 v7, v58, v3
	v_mul_f32_e32 v8, v59, v3
	ds_bpermute_b32 v7, v193, v7
	ds_bpermute_b32 v8, v193, v8
	v_cmp_gt_u32_e32 vcc, 32, v199
	v_add3_u32 v2, 0, v2, v214
	v_add_u32_e32 v2, 0xd800, v2
	s_waitcnt lgkmcnt(3)
	v_cndmask_b32_e64 v6, v4, 0, vcc
	s_waitcnt lgkmcnt(2)
	v_cndmask_b32_e32 v4, v5, v4, vcc
	v_fmac_f32_e32 v6, v121, v3
	v_fmac_f32_e32 v4, v101, v3
	ds_write2_b32 v2, v6, v4 offset1:2
	s_waitcnt lgkmcnt(2)
	v_cndmask_b32_e32 v4, v7, v5, vcc
	s_waitcnt lgkmcnt(1)
	v_cndmask_b32_e32 v5, v8, v7, vcc
	v_mul_f32_e32 v6, v60, v3
	v_mul_f32_e32 v7, v61, v3
	ds_bpermute_b32 v6, v193, v6
	ds_bpermute_b32 v7, v193, v7
	v_fmac_f32_e32 v4, v100, v3
	v_fmac_f32_e32 v5, v99, v3
	ds_write2_b32 v2, v4, v5 offset0:4 offset1:6
	s_waitcnt lgkmcnt(2)
	v_cndmask_b32_e32 v4, v6, v8, vcc
	s_waitcnt lgkmcnt(1)
	v_cndmask_b32_e32 v5, v7, v6, vcc
	v_fmac_f32_e32 v4, v97, v3
	v_fmac_f32_e32 v5, v98, v3
	ds_write2_b32 v2, v4, v5 offset0:8 offset1:10
	v_mul_f32_e32 v4, v62, v3
	v_sub_f32_e32 v1, v1, v1
	ds_bpermute_b32 v4, v193, v4
	v_exp_f32_e32 v1, v1
	v_mul_f32_e32 v5, v63, v3
	ds_bpermute_b32 v5, v193, v5
	v_lshlrev_b32_e32 v186, 5, v211
	v_mul_f32_e32 v1, v1, v218
	s_waitcnt lgkmcnt(1)
	v_cndmask_b32_e32 v6, v4, v7, vcc
	v_mul_f32_e32 v7, v18, v1
	ds_bpermute_b32 v7, v193, v7
	s_waitcnt lgkmcnt(1)
	v_cndmask_b32_e32 v4, v5, v4, vcc
	v_mul_f32_e32 v8, v19, v1
	v_fmac_f32_e32 v6, v55, v3
	ds_bpermute_b32 v8, v193, v8
	v_fmac_f32_e32 v4, v0, v3
	ds_write2_b32 v2, v6, v4 offset0:12 offset1:14
	s_waitcnt lgkmcnt(2)
	v_cndmask_b32_e32 v0, v7, v5, vcc
	v_mul_f32_e32 v4, v20, v1
	v_mul_f32_e32 v5, v30, v1
	ds_bpermute_b32 v4, v193, v4
	ds_bpermute_b32 v5, v193, v5
	s_waitcnt lgkmcnt(3)
	v_cndmask_b32_e32 v3, v8, v7, vcc
	v_fmac_f32_e32 v0, v50, v1
	v_fmac_f32_e32 v3, v21, v1
	ds_write2_b32 v2, v0, v3 offset0:16 offset1:18
	s_waitcnt lgkmcnt(2)
	v_cndmask_b32_e32 v0, v4, v8, vcc
	s_waitcnt lgkmcnt(1)
	v_cndmask_b32_e32 v3, v5, v4, vcc
	v_mul_f32_e32 v4, v110, v1
	v_mul_f32_e32 v6, v111, v1
	ds_bpermute_b32 v4, v193, v4
	ds_bpermute_b32 v6, v193, v6
	v_fmac_f32_e32 v0, v118, v1
	v_fmac_f32_e32 v3, v119, v1
	ds_write2_b32 v2, v0, v3 offset0:20 offset1:22
	s_waitcnt lgkmcnt(2)
	v_cndmask_b32_e32 v0, v4, v5, vcc
	s_waitcnt lgkmcnt(1)
	v_cndmask_b32_e32 v3, v6, v4, vcc
	v_mul_f32_e32 v4, v113, v1
	v_mul_f32_e32 v5, v117, v1
	ds_bpermute_b32 v4, v193, v4
	ds_bpermute_b32 v5, v193, v5
	v_fmac_f32_e32 v0, v31, v1
	v_fmac_f32_e32 v3, v51, v1
	ds_write2_b32 v2, v0, v3 offset0:24 offset1:26
	s_waitcnt lgkmcnt(2)
	v_cndmask_b32_e32 v0, v4, v6, vcc
	s_waitcnt lgkmcnt(1)
	v_cndmask_b32_e32 v3, v5, v4, vcc
	v_fmac_f32_e32 v0, v112, v1
	v_fmac_f32_e32 v3, v114, v1
	v_readlane_b32 s9, v253, 0
	ds_write2_b32 v2, v0, v3 offset0:28 offset1:30
	s_waitcnt lgkmcnt(0)
	v_lshl_add_u64 v[0:1], v[186:187], 2, s[8:9]
	v_lshlrev_b32_e32 v186, 2, v217
	v_lshl_add_u64 v[4:5], v[0:1], 0, v[186:187]
	s_mov_b64 s[8:9], 0x40000
	v_add_co_u32_e32 v6, vcc, 0x40000, v4
	v_lshl_add_u64 v[0:1], v[4:5], 0, s[8:9]
	s_nop 0
	v_addc_co_u32_e32 v7, vcc, 0, v5, vcc
	s_barrier
	global_load_dwordx4 v[16:19], v[4:5], off offset:16
	global_load_dwordx4 v[24:27], v[4:5], off
	global_load_dwordx4 v[28:31], v[6:7], off
	global_load_dwordx4 v[20:23], v[0:1], off offset:16
	s_nop 0
	global_load_dwordx4 v[0:3], v[4:5], off offset:80
	global_load_dwordx4 v[8:11], v[4:5], off offset:64
	s_mov_b64 s[8:9], 0x40040
	v_lshl_add_u64 v[4:5], v[4:5], 0, s[8:9]
	global_load_dwordx4 v[12:15], v[6:7], off offset:64
	s_nop 0
	global_load_dwordx4 v[4:7], v[4:5], off offset:16
	s_lshl_b32 s10, s71, 20
	v_readlane_b32 s1, v254, 53
	s_add_u32 s11, s1, s10
	v_readlane_b32 s1, v254, 54
	s_addc_u32 s12, s1, 0
	s_lshl_b32 s13, s70, 7
	s_add_u32 s78, s11, s13
	s_addc_u32 s79, s12, 0
	v_readlane_b32 s1, v254, 59
	s_add_u32 s10, s1, s10
	v_readlane_b32 s1, v254, 60
	s_addc_u32 s11, s1, 0
	s_add_u32 s80, s10, s13
	s_addc_u32 s81, s11, 0
	s_lshr_b32 s6, s3, 1
	s_add_i32 s6, s6, -8
	s_max_i32 s6, s6, 0
	v_lshl_add_u32 v250, s6, 6, v212
	v_lshlrev_b32_e32 v250, 9, v250
	v_add_u32_e32 v250, v250, v192
	v_add_u32_e32 v251, 0x8000, v250
	global_load_dwordx4 v[236:239], v250, s[78:79] offset:256
	global_load_dwordx4 v[240:243], v250, s[80:81] offset:256
	global_load_dwordx4 v[244:247], v251, s[78:79] offset:256
	global_load_dwordx4 v[248:251], v251, s[80:81] offset:256
	v_cmp_eq_u32_e32 vcc, 0, v136
	s_and_saveexec_b64 s[8:9], vcc
	s_cbranch_execz .LBB0_905
	v_readlane_b32 s1, v255, 10
	s_nop 1
	v_mov_b32_e32 v48, s1
	ds_write_b32 v48, v187
